# v25
# speedup vs baseline: 1.0508x; 1.0048x over previous
.LBB0_736:
	s_waitcnt lgkmcnt(0)
	s_add_u32 s22, s4, s20
	s_addc_u32 s23, s5, s21
	global_load_dwordx4 v[6:9], v209, s[22:23]
	s_add_u32 s22, s6, s20
	s_addc_u32 s23, s7, s21
	s_add_u32 s24, s8, s20
	s_addc_u32 s25, s9, s21
	global_load_dwordx4 v[10:13], v209, s[24:25]
	s_add_u32 s24, s10, s20
	s_addc_u32 s25, s11, s21
	global_load_dwordx4 v[14:17], v209, s[24:25]
	s_add_u32 s24, s16, s20
	s_addc_u32 s25, s17, s21
	global_load_dwordx4 v[18:21], v209, s[24:25]
	s_add_u32 s24, s18, s20
	s_addc_u32 s25, s19, s21
	global_load_dwordx4 v[22:25], v209, s[24:25]
	global_load_dwordx4 v[26:29], v209, s[22:23]
	s_add_u32 s20, s20, 16
	s_addc_u32 s21, s21, 0
	s_cmpk_eq_i32 s20, 0x100
	s_waitcnt vmcnt(5)
	v_max3_f32 v4, v4, |v6|, |v7|
	v_max3_f32 v4, v4, |v8|, |v9|
	s_waitcnt vmcnt(4)
	v_mov_b32_e32 v6, v10
	v_mov_b32_e32 v8, v12
	s_waitcnt vmcnt(3)
	v_mov_b32_e32 v10, v14
	v_mov_b32_e32 v12, v16
	s_waitcnt vmcnt(2)
	v_mov_b32_e32 v7, v18
	v_mov_b32_e32 v18, v11
	s_waitcnt vmcnt(1)
	v_mov_b32_e32 v11, v22
	v_mov_b32_e32 v22, v15
	v_pk_fma_f32 v[0:1], v[6:7], v[10:11], v[0:1]
	v_mov_b32_e32 v9, v20
	v_mov_b32_e32 v20, v13
	v_mov_b32_e32 v13, v24
	v_pk_fma_f32 v[0:1], v[18:19], v[22:23], v[0:1]
	s_waitcnt vmcnt(0)
	v_max3_f32 v3, v3, |v26|, |v27|
	v_mov_b32_e32 v24, v17
	v_pk_fma_f32 v[0:1], v[8:9], v[12:13], v[0:1]
	v_max3_f32 v3, v3, |v28|, |v29|
	v_pk_fma_f32 v[0:1], v[20:21], v[24:25], v[0:1]
	s_cbranch_scc0 .LBB0_736
	v_mul_f32_e32 v5, 0x3fb8aa3b, v0
	v_rndne_f32_e32 v6, v5
	s_mov_b32 s4, 0x3fb8aa3b
	v_sub_f32_e32 v7, v5, v6
	v_fma_f32 v5, v0, s4, -v5
	v_fmac_f32_e32 v5, 0x32a5705f, v0
	v_add_f32_e32 v5, v7, v5
	v_cvt_i32_f32_e32 v6, v6
	v_exp_f32_e32 v5, v5
	s_mov_b32 s5, 0x42b17218
	s_mov_b32 s53, s2
	v_ldexp_f32 v5, v5, v6
	v_mul_f32_e32 v6, 0x3fb8aa3b, v1
	v_rndne_f32_e32 v7, v6
	v_sub_f32_e32 v8, v6, v7
	v_fma_f32 v6, v1, s4, -v6
	v_fmac_f32_e32 v6, 0x32a5705f, v1
	v_add_f32_e32 v6, v8, v6
	v_exp_f32_e32 v6, v6
	v_cvt_i32_f32_e32 v7, v7
	s_mov_b32 s4, 0xc2ce8ed0
	v_cmp_ngt_f32_e32 vcc, s4, v0
	v_mov_b32_e32 v8, 0x7f800000
	s_cmpk_gt_i32 s53, 0xfff
	v_cndmask_b32_e32 v5, 0, v5, vcc
	v_cmp_nlt_f32_e32 vcc, s5, v0
	s_nop 1
	v_cndmask_b32_e32 v0, v8, v5, vcc
	v_ldexp_f32 v5, v6, v7
	v_cmp_ngt_f32_e32 vcc, s4, v1
	s_nop 1
	v_cndmask_b32_e32 v5, 0, v5, vcc
	v_cmp_nlt_f32_e32 vcc, s5, v1
	s_nop 1
	v_cndmask_b32_e32 v1, v8, v5, vcc
	v_sub_f32_e32 v0, v0, v1
	s_nop 0
	v_readfirstlane_b32 s5, v0
	v_mul_f32_e32 v0, 0x4138aa3b, v4
	v_mul_f32_e32 v0, v3, v0
	s_nop 0
	v_readfirstlane_b32 s4, v0
	s_cbranch_scc1 .LBB0_749
	s_add_u32 s8, s54, 0x22000000
	v_or_b32_e32 v0, s33, v2
	s_addc_u32 s9, s55, 0
	s_add_u32 s10, s54, 0x12000000
	v_mov_b32_e32 v1, 0x3eb60549
	s_load_dwordx2 s[34:35], s[0:1], 0xe8
	v_ashrrev_i32_e32 v5, 8, v0
	s_addc_u32 s11, s55, 0
	v_add_f32_e32 v145, s5, v1
	v_lshlrev_b32_e32 v148, 6, v5
	v_mul_i32_i24_e32 v168, 0x2400, v5
	s_xor_b32 s16, s4, 0x80000000
	v_cmp_eq_u32_e64 s[4:5], 1, v5
	s_movk_i32 s6, 0x100
	v_lshlrev_b32_e32 v5, 8, v0
	v_ashrrev_i32_e32 v147, 3, v0
	v_lshlrev_b32_e32 v1, 3, v0
	v_bfe_u32 v3, v0, 6, 2
	v_and_b32_e32 v4, 63, v2
	v_cmp_gt_u32_e64 s[6:7], s6, v0
	v_and_b32_e32 v8, 0xc000, v5
	v_lshlrev_b32_e32 v0, 4, v0
	v_and_b32_e32 v146, 56, v1
	v_and_b32_e32 v1, 31, v2
	v_bfe_u32 v6, v2, 5, 1
	v_lshlrev_b32_e32 v166, 5, v3
	v_lshl_add_u32 v4, v4, 2, 0
	v_add_u32_e32 v9, 0, v8
	v_and_b32_e32 v208, 0xf0, v0
	v_or_b32_e32 v167, v166, v1
	v_mul_u32_u24_e32 v169, 0x90, v1
	v_mul_u32_u24_e32 v10, 0x110, v1
	v_add_u32_e32 v11, v9, v208
	v_lshl_add_u64 v[0:1], s[54:55], 0, v[208:209]
	v_lshl_add_u32 v172, v3, 14, v4
	v_lshlrev_b32_e32 v208, 4, v6
	v_lshrrev_b32_e32 v3, 4, v2
	v_and_b32_e32 v151, 63, v147
	s_mov_b64 s[18:19], 0x2a000000
	s_waitcnt lgkmcnt(0)
	v_lshl_add_u64 v[154:155], s[34:35], 0, v[208:209]
	v_and_b32_e32 v7, 31, v2
	v_lshlrev_b32_e32 v7, 4, v7
	global_load_dword v175, v7, s[34:35]
	global_load_dword v178, v7, s[34:35] offset:4
	global_load_dword v182, v7, s[34:35] offset:8
	global_load_dword v150, v7, s[34:35] offset:12
	v_add_u32_e32 v7, 0x1f000, v7
	v_add_u32_e32 v154, 0x1f000, v208
	s_waitcnt vmcnt(0)
	ds_write_b32 v7, v175
	ds_write_b32 v7, v178 offset:4
	ds_write_b32 v7, v182 offset:8
	ds_write_b32 v7, v150 offset:12
	s_waitcnt lgkmcnt(0)
	s_barrier
	v_bfe_u32 v175, v2, 4, 2
	v_or_b32_e32 v178, 12, v3
	s_movk_i32 s34, 0x110
	v_or_b32_e32 v182, 28, v3
	v_bitop3_b32 v2, v2, 7, s33 bitop3:0xc8
	v_lshlrev_b32_e32 v150, 3, v6
	v_mul_u32_u24_e32 v7, 0x48, v151
	v_lshlrev_b32_e32 v170, 2, v6
	v_lshl_add_u64 v[152:153], v[0:1], 0, s[18:19]
	s_movk_i32 s17, 0x90
	v_or_b32_e32 v0, 0x3f00, v5
	v_mul_u32_u24_e32 v1, 0x110, v175
	v_mul_lo_u32 v5, v178, s34
	v_mul_lo_u32 v3, v182, s34
	v_lshlrev_b32_e32 v158, 4, v2
	v_lshlrev_b32_e32 v2, 11, v151
	v_ashrrev_i32_e32 v149, 31, v148
	v_mul_lo_u32 v171, v147, s17
	s_mov_b32 s17, s16
	s_mov_b32 s18, s16
	s_mov_b32 s19, s16
	s_mov_b32 s20, s16
	s_mov_b32 s21, s16
	s_mov_b32 s22, s16
	s_mov_b32 s23, s16
	s_mov_b32 s24, s16
	s_mov_b32 s25, s16
	s_mov_b32 s26, s16
	s_mov_b32 s27, s16
	s_mov_b32 s28, s16
	s_mov_b32 s29, s16
	s_mov_b32 s30, s16
	s_mov_b32 s31, s16
	v_add_u32_e32 v173, v4, v8
	v_add3_u32 v174, v9, v10, v150
	v_or_b32_e32 v176, 4, v175
	v_or_b32_e32 v177, 8, v175
	v_or_b32_e32 v179, 16, v175
	v_or_b32_e32 v180, 20, v175
	v_or_b32_e32 v181, 24, v175
	v_mov_b32_e32 v156, v145
	v_mov_b32_e32 v157, v145
	v_sub_u32_e32 v183, v167, v170
	v_mov_b32_e32 v159, v209
	s_lshl_b32 s58, s53, 1
	v_lshlrev_b32_e32 v160, 1, v146
	v_lshlrev_b32_e32 v184, 1, v2
	v_lshlrev_b32_e32 v185, 1, v7
	v_add_u32_e32 v186, v4, v0
	v_add_u32_e32 v187, v11, v1
	v_add_u32_e32 v188, v11, v5
	v_add_u32_e32 v189, v11, v3
	s_branch .LBB0_740

.LBB0_747:
	s_or_b64 exec, exec, s[56:57]
	s_waitcnt lgkmcnt(0)
	s_barrier
	s_and_saveexec_b64 s[56:57], s[6:7]
	s_cbranch_execz .LBB0_739
	ds_read2st64_b32 v[68:69], v173 offset1:1
	v_mov_b32_e32 v144, v48
	s_lshl_b32 s36, s46, 1
	s_waitcnt lgkmcnt(0)
	v_mov_b32_e32 v65, v68
	v_pk_mul_f32 v[70:71], v[144:145], v[64:65]
	v_mov_b32_e32 v144, v49
	v_mov_b32_e32 v65, v69
	v_pk_mul_f32 v[68:69], v[144:145], v[64:65]
	v_mov_b32_e32 v144, v50
	v_sub_f32_e32 v49, v68, v69
	ds_read2st64_b32 v[68:69], v173 offset0:2 offset1:3
	v_sub_f32_e32 v48, v70, v71
	s_waitcnt lgkmcnt(0)
	v_mov_b32_e32 v65, v68
	v_pk_mul_f32 v[70:71], v[144:145], v[64:65]
	v_mov_b32_e32 v144, v51
	v_mov_b32_e32 v65, v69
	v_pk_mul_f32 v[68:69], v[144:145], v[64:65]
	v_mov_b32_e32 v144, v52
	v_sub_f32_e32 v51, v68, v69
	ds_read2st64_b32 v[68:69], v173 offset0:4 offset1:5
	v_sub_f32_e32 v50, v70, v71
	s_waitcnt lgkmcnt(0)
	v_mov_b32_e32 v65, v68
	v_pk_mul_f32 v[70:71], v[144:145], v[64:65]
	v_mov_b32_e32 v144, v53
	v_mov_b32_e32 v65, v69
	v_pk_mul_f32 v[68:69], v[144:145], v[64:65]
	v_mov_b32_e32 v144, v54
	v_sub_f32_e32 v53, v68, v69
	ds_read2st64_b32 v[68:69], v173 offset0:6 offset1:7
	v_sub_f32_e32 v52, v70, v71
	s_waitcnt lgkmcnt(0)
	v_mov_b32_e32 v65, v68
	v_pk_mul_f32 v[70:71], v[144:145], v[64:65]
	v_mov_b32_e32 v144, v55
	v_mov_b32_e32 v65, v69
	v_pk_mul_f32 v[68:69], v[144:145], v[64:65]
	v_mov_b32_e32 v144, v56
	v_sub_f32_e32 v55, v68, v69
	ds_read2st64_b32 v[68:69], v173 offset0:8 offset1:9
	v_sub_f32_e32 v54, v70, v71
	s_waitcnt lgkmcnt(0)
	v_mov_b32_e32 v65, v68
	v_pk_mul_f32 v[70:71], v[144:145], v[64:65]
	v_mov_b32_e32 v144, v57
	v_mov_b32_e32 v65, v69
	v_pk_mul_f32 v[68:69], v[144:145], v[64:65]
	v_mov_b32_e32 v144, v58
	v_sub_f32_e32 v57, v68, v69
	ds_read2st64_b32 v[68:69], v173 offset0:10 offset1:11
	v_sub_f32_e32 v56, v70, v71
	s_waitcnt lgkmcnt(0)
	v_mov_b32_e32 v65, v68
	v_pk_mul_f32 v[70:71], v[144:145], v[64:65]
	v_mov_b32_e32 v144, v59
	v_mov_b32_e32 v65, v69
	v_pk_mul_f32 v[68:69], v[144:145], v[64:65]
	v_mov_b32_e32 v144, v60
	v_sub_f32_e32 v59, v68, v69
	ds_read2st64_b32 v[68:69], v173 offset0:12 offset1:13
	v_sub_f32_e32 v58, v70, v71
	s_waitcnt lgkmcnt(0)
	v_mov_b32_e32 v65, v68
	v_pk_mul_f32 v[70:71], v[144:145], v[64:65]
	v_mov_b32_e32 v144, v61
	v_mov_b32_e32 v65, v69
	v_pk_mul_f32 v[68:69], v[144:145], v[64:65]
	v_mov_b32_e32 v144, v62
	v_sub_f32_e32 v61, v68, v69
	ds_read2st64_b32 v[68:69], v173 offset0:14 offset1:15
	v_sub_f32_e32 v60, v70, v71
	s_waitcnt lgkmcnt(0)
	v_mov_b32_e32 v65, v68
	v_pk_mul_f32 v[70:71], v[144:145], v[64:65]
	v_mov_b32_e32 v144, v63
	v_mov_b32_e32 v65, v69
	v_pk_mul_f32 v[68:69], v[144:145], v[64:65]
	v_mov_b32_e32 v144, v32
	v_sub_f32_e32 v63, v68, v69
	ds_read2st64_b32 v[68:69], v173 offset0:16 offset1:17
	v_sub_f32_e32 v62, v70, v71
	s_waitcnt lgkmcnt(0)
	v_mov_b32_e32 v65, v68
	v_pk_mul_f32 v[70:71], v[144:145], v[64:65]
	v_mov_b32_e32 v144, v33
	v_mov_b32_e32 v65, v69
	v_pk_mul_f32 v[68:69], v[144:145], v[64:65]
	v_mov_b32_e32 v144, v34
	v_sub_f32_e32 v33, v68, v69
	ds_read2st64_b32 v[68:69], v173 offset0:18 offset1:19
	v_sub_f32_e32 v32, v70, v71
	s_waitcnt lgkmcnt(0)
	v_mov_b32_e32 v65, v68
	v_pk_mul_f32 v[70:71], v[144:145], v[64:65]
	v_mov_b32_e32 v144, v35
	v_mov_b32_e32 v65, v69
	v_pk_mul_f32 v[68:69], v[144:145], v[64:65]
	v_mov_b32_e32 v144, v36
	v_sub_f32_e32 v35, v68, v69
	ds_read2st64_b32 v[68:69], v173 offset0:20 offset1:21
	v_sub_f32_e32 v34, v70, v71
	s_waitcnt lgkmcnt(0)
	v_mov_b32_e32 v65, v68
	v_pk_mul_f32 v[70:71], v[144:145], v[64:65]
	v_mov_b32_e32 v65, v69
	ds_read2st64_b32 v[68:69], v173 offset0:22 offset1:23
	v_mov_b32_e32 v144, v37
	v_pk_mul_f32 v[36:37], v[144:145], v[64:65]
	v_mov_b32_e32 v144, v38
	v_sub_f32_e32 v66, v70, v71
	s_waitcnt lgkmcnt(0)
	v_mov_b32_e32 v65, v68
	v_pk_mul_f32 v[70:71], v[144:145], v[64:65]
	v_mov_b32_e32 v144, v39
	v_sub_f32_e32 v68, v70, v71
	ds_read2st64_b32 v[70:71], v173 offset0:24 offset1:25
	v_mov_b32_e32 v65, v69
	v_pk_mul_f32 v[38:39], v[144:145], v[64:65]
	v_mov_b32_e32 v144, v40
	v_sub_f32_e32 v36, v36, v37
	s_waitcnt lgkmcnt(0)
	v_mov_b32_e32 v65, v70
	v_pk_mul_f32 v[72:73], v[144:145], v[64:65]
	v_mov_b32_e32 v65, v71
	ds_read2st64_b32 v[70:71], v173 offset0:26 offset1:27
	v_mov_b32_e32 v144, v41
	v_pk_mul_f32 v[40:41], v[144:145], v[64:65]
	v_mov_b32_e32 v144, v42
	v_sub_f32_e32 v37, v40, v41
	s_waitcnt lgkmcnt(0)
	v_mov_b32_e32 v65, v70
	v_pk_mul_f32 v[40:41], v[144:145], v[64:65]
	v_mov_b32_e32 v65, v71
	ds_read2st64_b32 v[70:71], v173 offset0:28 offset1:29
	v_mov_b32_e32 v144, v43
	v_pk_mul_f32 v[42:43], v[144:145], v[64:65]
	v_mov_b32_e32 v144, v44
	v_sub_f32_e32 v41, v40, v41
	s_waitcnt lgkmcnt(0)
	v_mov_b32_e32 v65, v70
	v_sub_f32_e32 v40, v42, v43
	v_pk_mul_f32 v[42:43], v[144:145], v[64:65]
	v_mov_b32_e32 v144, v45
	v_mov_b32_e32 v65, v71
	v_pk_mul_f32 v[44:45], v[144:145], v[64:65]
	v_sub_f32_e32 v43, v42, v43
	v_sub_f32_e32 v42, v44, v45
	ds_read2st64_b32 v[44:45], v173 offset0:30 offset1:31
	v_mov_b32_e32 v144, v46
	v_sub_f32_e32 v39, v38, v39
	v_sub_f32_e32 v38, v72, v73
	s_waitcnt lgkmcnt(0)
	v_mov_b32_e32 v65, v44
	v_pk_mul_f32 v[70:71], v[144:145], v[64:65]
	v_mov_b32_e32 v144, v47
	v_sub_f32_e32 v69, v70, v71
	ds_read2st64_b32 v[70:71], v173 offset0:32 offset1:33
	v_mov_b32_e32 v65, v45
	v_pk_mul_f32 v[44:45], v[144:145], v[64:65]
	v_mov_b32_e32 v144, v16
	v_sub_f32_e32 v46, v44, v45
	s_waitcnt lgkmcnt(0)
	v_mov_b32_e32 v65, v70
	v_pk_mul_f32 v[44:45], v[144:145], v[64:65]
	v_mov_b32_e32 v144, v17
	v_mov_b32_e32 v65, v71
	v_pk_mul_f32 v[16:17], v[144:145], v[64:65]
	v_sub_f32_e32 v45, v44, v45
	v_sub_f32_e32 v44, v16, v17
	ds_read2st64_b32 v[16:17], v173 offset0:34 offset1:35
	v_mov_b32_e32 v144, v18
	s_waitcnt lgkmcnt(0)
	v_mov_b32_e32 v65, v16
	v_pk_mul_f32 v[70:71], v[144:145], v[64:65]
	v_mov_b32_e32 v144, v19
	v_mov_b32_e32 v65, v17
	v_pk_mul_f32 v[16:17], v[144:145], v[64:65]
	v_mov_b32_e32 v144, v20
	v_sub_f32_e32 v18, v16, v17
	ds_read2st64_b32 v[16:17], v173 offset0:36 offset1:37
	v_sub_f32_e32 v47, v70, v71
	s_waitcnt lgkmcnt(0)
	v_mov_b32_e32 v65, v16
	v_pk_mul_f32 v[70:71], v[144:145], v[64:65]
	v_mov_b32_e32 v144, v21
	v_mov_b32_e32 v65, v17
	v_pk_mul_f32 v[16:17], v[144:145], v[64:65]
	v_mov_b32_e32 v144, v22
	v_sub_f32_e32 v19, v16, v17
	ds_read2st64_b32 v[16:17], v173 offset0:38 offset1:39
	v_sub_f32_e32 v20, v70, v71
	s_waitcnt lgkmcnt(0)
	v_mov_b32_e32 v65, v16
	v_pk_mul_f32 v[70:71], v[144:145], v[64:65]
	v_mov_b32_e32 v144, v23
	v_mov_b32_e32 v65, v17
	v_pk_mul_f32 v[16:17], v[144:145], v[64:65]
	v_mov_b32_e32 v144, v24
	v_sub_f32_e32 v23, v16, v17
	ds_read2st64_b32 v[16:17], v173 offset0:40 offset1:41
	v_sub_f32_e32 v70, v70, v71
	s_waitcnt lgkmcnt(0)
	v_mov_b32_e32 v65, v16
	v_pk_mul_f32 v[72:73], v[144:145], v[64:65]
	v_mov_b32_e32 v144, v25
	v_mov_b32_e32 v65, v17
	v_pk_mul_f32 v[16:17], v[144:145], v[64:65]
	v_mov_b32_e32 v144, v26
	v_sub_f32_e32 v21, v16, v17
	ds_read2st64_b32 v[16:17], v173 offset0:42 offset1:43
	v_sub_f32_e32 v22, v72, v73
	s_waitcnt lgkmcnt(0)
	v_mov_b32_e32 v65, v16
	v_pk_mul_f32 v[24:25], v[144:145], v[64:65]
	v_mov_b32_e32 v144, v27
	v_mov_b32_e32 v65, v17
	v_pk_mul_f32 v[16:17], v[144:145], v[64:65]
	v_sub_f32_e32 v25, v24, v25
	v_sub_f32_e32 v24, v16, v17
	ds_read2st64_b32 v[16:17], v173 offset0:44 offset1:45
	v_mov_b32_e32 v144, v28
	s_waitcnt lgkmcnt(0)
	v_mov_b32_e32 v65, v16
	v_pk_mul_f32 v[26:27], v[144:145], v[64:65]
	v_mov_b32_e32 v144, v29
	v_mov_b32_e32 v65, v17
	v_pk_mul_f32 v[16:17], v[144:145], v[64:65]
	v_sub_f32_e32 v27, v26, v27
	v_sub_f32_e32 v26, v16, v17
	ds_read2st64_b32 v[16:17], v173 offset0:46 offset1:47
	v_mov_b32_e32 v144, v30
	s_waitcnt lgkmcnt(0)
	v_mov_b32_e32 v65, v16
	v_pk_mul_f32 v[28:29], v[144:145], v[64:65]
	v_mov_b32_e32 v144, v31
	v_mov_b32_e32 v65, v17
	v_pk_mul_f32 v[16:17], v[144:145], v[64:65]
	v_mov_b32_e32 v144, v0
	v_sub_f32_e32 v30, v16, v17
	ds_read2st64_b32 v[16:17], v173 offset0:48 offset1:49
	v_sub_f32_e32 v71, v28, v29
	s_waitcnt lgkmcnt(0)
	v_mov_b32_e32 v65, v16
	v_pk_mul_f32 v[28:29], v[144:145], v[64:65]
	v_mov_b32_e32 v144, v1
	v_mov_b32_e32 v65, v17
	v_pk_mul_f32 v[0:1], v[144:145], v[64:65]
	v_sub_f32_e32 v29, v28, v29
	v_sub_f32_e32 v28, v0, v1
	ds_read2st64_b32 v[0:1], v173 offset0:50 offset1:51
	v_mov_b32_e32 v144, v2
	s_waitcnt lgkmcnt(0)
	v_mov_b32_e32 v65, v0
	v_pk_mul_f32 v[16:17], v[144:145], v[64:65]
	v_mov_b32_e32 v144, v3
	v_mov_b32_e32 v65, v1
	v_pk_mul_f32 v[0:1], v[144:145], v[64:65]
	v_mov_b32_e32 v144, v4
	v_sub_f32_e32 v31, v0, v1
	ds_read2st64_b32 v[0:1], v173 offset0:52 offset1:53
	v_sub_f32_e32 v72, v16, v17
	s_waitcnt lgkmcnt(0)
	v_mov_b32_e32 v65, v0
	v_pk_mul_f32 v[2:3], v[144:145], v[64:65]
	v_mov_b32_e32 v144, v5
	v_mov_b32_e32 v65, v1
	v_pk_mul_f32 v[0:1], v[144:145], v[64:65]
	v_mov_b32_e32 v144, v6
	v_sub_f32_e32 v73, v0, v1
	ds_read2st64_b32 v[0:1], v173 offset0:54 offset1:55
	v_sub_f32_e32 v74, v2, v3
	s_waitcnt lgkmcnt(0)
	v_mov_b32_e32 v65, v0
	v_pk_mul_f32 v[2:3], v[144:145], v[64:65]
	v_mov_b32_e32 v144, v7
	v_mov_b32_e32 v65, v1
	v_pk_mul_f32 v[0:1], v[144:145], v[64:65]
	v_mov_b32_e32 v4, v2
	v_mov_b32_e32 v5, v0
	v_mov_b32_e32 v0, v3
	ds_read2st64_b32 v[2:3], v173 offset0:56 offset1:57
	v_mov_b32_e32 v144, v8
	v_pk_add_f32 v[6:7], v[4:5], v[0:1] neg_lo:[0,1] neg_hi:[0,1]
	s_waitcnt lgkmcnt(0)
	v_mov_b32_e32 v65, v2
	v_pk_mul_f32 v[4:5], v[144:145], v[64:65]
	v_mov_b32_e32 v144, v9
	v_mov_b32_e32 v65, v3
	v_pk_mul_f32 v[2:3], v[144:145], v[64:65]
	v_mov_b32_e32 v8, v4
	v_mov_b32_e32 v9, v2
	v_mov_b32_e32 v2, v5
	v_pk_add_f32 v[4:5], v[8:9], v[2:3] neg_lo:[0,1] neg_hi:[0,1]
	ds_read2st64_b32 v[8:9], v173 offset0:58 offset1:59
	v_mov_b32_e32 v144, v10
	v_pk_mul_f32 v[0:1], v[6:7], v[6:7]
	v_pk_mul_f32 v[2:3], v[4:5], v[4:5]
	s_waitcnt lgkmcnt(0)
	v_mov_b32_e32 v65, v8
	v_pk_mul_f32 v[16:17], v[144:145], v[64:65]
	v_mov_b32_e32 v144, v11
	v_mov_b32_e32 v65, v9
	v_pk_mul_f32 v[8:9], v[144:145], v[64:65]
	v_mov_b32_e32 v10, v16
	v_mov_b32_e32 v11, v8
	v_mov_b32_e32 v8, v17
	v_pk_add_f32 v[8:9], v[10:11], v[8:9] neg_lo:[0,1] neg_hi:[0,1]
	ds_read2st64_b32 v[10:11], v173 offset0:60 offset1:61
	v_mov_b32_e32 v144, v12
	v_pk_mul_f32 v[16:17], v[8:9], v[8:9]
	s_waitcnt lgkmcnt(0)
	v_mov_b32_e32 v65, v10
	v_pk_mul_f32 v[76:77], v[144:145], v[64:65]
	v_mov_b32_e32 v144, v13
	v_mov_b32_e32 v65, v11
	v_pk_mul_f32 v[10:11], v[144:145], v[64:65]
	v_mov_b32_e32 v12, v76
	v_mov_b32_e32 v13, v10
	v_mov_b32_e32 v10, v77
	v_pk_add_f32 v[10:11], v[12:13], v[10:11] neg_lo:[0,1] neg_hi:[0,1]
	ds_read_b32 v12, v173 offset:15872
	ds_read_b32 v13, v186
	v_pk_mul_f32 v[76:77], v[10:11], v[10:11]
	s_waitcnt lgkmcnt(0)
	v_pk_mul_f32 v[12:13], v[156:157], v[12:13]
	s_nop 0
	v_pk_fma_f32 v[12:13], v[14:15], v[64:65], v[12:13] op_sel_hi:[1,0,1] neg_lo:[0,0,1] neg_hi:[0,0,1]
	v_mul_f32_e32 v64, v48, v48
	v_fmac_f32_e32 v64, v49, v49
	v_fmac_f32_e32 v64, v50, v50
	v_fmac_f32_e32 v64, v51, v51
	v_fmac_f32_e32 v64, v52, v52
	v_fmac_f32_e32 v64, v53, v53
	v_fmac_f32_e32 v64, v54, v54
	v_fmac_f32_e32 v64, v55, v55
	v_fmac_f32_e32 v64, v56, v56
	v_fmac_f32_e32 v64, v57, v57
	v_fmac_f32_e32 v64, v58, v58
	v_fmac_f32_e32 v64, v59, v59
	v_fmac_f32_e32 v64, v60, v60
	v_fmac_f32_e32 v64, v61, v61
	v_fmac_f32_e32 v64, v62, v62
	v_fmac_f32_e32 v64, v63, v63
	v_fmac_f32_e32 v64, v32, v32
	v_fmac_f32_e32 v64, v33, v33
	v_fmac_f32_e32 v64, v34, v34
	v_fmac_f32_e32 v64, v35, v35
	v_fmac_f32_e32 v64, v66, v66
	v_fmac_f32_e32 v64, v36, v36
	v_fmac_f32_e32 v64, v68, v68
	v_fmac_f32_e32 v64, v39, v39
	v_fmac_f32_e32 v64, v38, v38
	v_fmac_f32_e32 v64, v37, v37
	v_fmac_f32_e32 v64, v41, v41
	v_fmac_f32_e32 v64, v40, v40
	v_fmac_f32_e32 v64, v43, v43
	v_fmac_f32_e32 v64, v42, v42
	v_fmac_f32_e32 v64, v69, v69
	v_fmac_f32_e32 v64, v46, v46
	v_fmac_f32_e32 v64, v45, v45
	v_fmac_f32_e32 v64, v44, v44
	v_fmac_f32_e32 v64, v47, v47
	v_fmac_f32_e32 v64, v18, v18
	v_fmac_f32_e32 v64, v20, v20
	v_fmac_f32_e32 v64, v19, v19
	v_fmac_f32_e32 v64, v70, v70
	v_fmac_f32_e32 v64, v23, v23
	v_fmac_f32_e32 v64, v22, v22
	v_fmac_f32_e32 v64, v21, v21
	v_fmac_f32_e32 v64, v25, v25
	v_fmac_f32_e32 v64, v24, v24
	v_fmac_f32_e32 v64, v27, v27
	v_fmac_f32_e32 v64, v26, v26
	v_fmac_f32_e32 v64, v71, v71
	v_fmac_f32_e32 v64, v30, v30
	v_fmac_f32_e32 v64, v29, v29
	v_fmac_f32_e32 v64, v28, v28
	v_fmac_f32_e32 v64, v72, v72
	v_fmac_f32_e32 v64, v31, v31
	v_fmac_f32_e32 v64, v74, v74
	v_fmac_f32_e32 v64, v73, v73
	v_add_f32_e32 v0, v64, v0
	v_add_f32_e32 v0, v0, v1
	v_add_f32_e32 v0, v0, v2
	v_add_f32_e32 v0, v0, v3
	v_add_f32_e32 v0, v0, v16
	v_add_f32_e32 v0, v0, v17
	v_add_f32_e32 v0, v0, v76
	v_pk_mul_f32 v[14:15], v[12:13], v[12:13]
	v_add_f32_e32 v0, v0, v77
	v_add_f32_e32 v0, v0, v14
	v_add_f32_e32 v0, v0, v15
	ds_bpermute_b32 v1, v67, v0
	s_waitcnt lgkmcnt(0)
	v_add_f32_e32 v0, v0, v1
	v_fmamk_f32 v0, v0, 0x3c000000, v248
	v_cmp_gt_f32_e32 vcc, s97, v0
	v_mul_f32_e32 v1, 0x4b800000, v0
	s_nop 0
	v_cndmask_b32_e32 v0, v0, v1, vcc
	v_rsq_f32_e32 v0, v0
	s_nop 0
	v_mul_f32_e32 v1, 0x45800000, v0
	v_cndmask_b32_e32 v0, v0, v1, vcc
	v_mul_f32_e32 v14, 0x3f24fd5c, v0
	ds_read_b128 v[0:3], v154
	v_mul_f32_e32 v15, v48, v14
	v_mul_f32_e32 v4, v4, v14
	s_waitcnt lgkmcnt(0)
	v_mul_f32_e32 v0, v0, v15
	v_mul_f32_e32 v15, v49, v14
	v_mul_f32_e32 v1, v1, v15
	v_cvt_pk_bf16_f32 v0, v0, v1
	v_mul_f32_e32 v1, v50, v14
	v_mul_f32_e32 v1, v2, v1
	v_mul_f32_e32 v2, v51, v14
	v_mul_f32_e32 v2, v3, v2
	v_cvt_pk_bf16_f32 v1, v1, v2
	ds_write_b64 v174, v[0:1]
	ds_read_b128 v[0:3], v154 offset:32
	v_mul_f32_e32 v15, v52, v14
	s_waitcnt lgkmcnt(0)
	v_mul_f32_e32 v0, v0, v15
	v_mul_f32_e32 v15, v53, v14
	v_mul_f32_e32 v1, v1, v15
	v_cvt_pk_bf16_f32 v0, v0, v1
	v_mul_f32_e32 v1, v54, v14
	v_mul_f32_e32 v1, v2, v1
	v_mul_f32_e32 v2, v55, v14
	v_mul_f32_e32 v2, v3, v2
	v_cvt_pk_bf16_f32 v1, v1, v2
	ds_write_b64 v174, v[0:1] offset:16
	ds_read_b128 v[0:3], v154 offset:64
	v_mul_f32_e32 v15, v56, v14
	s_waitcnt lgkmcnt(0)
	v_mul_f32_e32 v0, v0, v15
	v_mul_f32_e32 v15, v57, v14
	v_mul_f32_e32 v1, v1, v15
	v_cvt_pk_bf16_f32 v0, v0, v1
	v_mul_f32_e32 v1, v58, v14
	v_mul_f32_e32 v1, v2, v1
	v_mul_f32_e32 v2, v59, v14
	v_mul_f32_e32 v2, v3, v2
	v_cvt_pk_bf16_f32 v1, v1, v2
	ds_write_b64 v174, v[0:1] offset:32
	ds_read_b128 v[0:3], v154 offset:96
	v_mul_f32_e32 v15, v60, v14
	s_waitcnt lgkmcnt(0)
	v_mul_f32_e32 v0, v0, v15
	v_mul_f32_e32 v15, v61, v14
	v_mul_f32_e32 v1, v1, v15
	v_cvt_pk_bf16_f32 v0, v0, v1
	v_mul_f32_e32 v1, v62, v14
	v_mul_f32_e32 v1, v2, v1
	v_mul_f32_e32 v2, v63, v14
	v_mul_f32_e32 v2, v3, v2
	v_cvt_pk_bf16_f32 v1, v1, v2
	ds_write_b64 v174, v[0:1] offset:48
	ds_read_b128 v[0:3], v154 offset:128
	v_mul_f32_e32 v15, v32, v14
	s_waitcnt lgkmcnt(0)
	v_mul_f32_e32 v0, v15, v0
	v_mul_f32_e32 v15, v33, v14
	v_mul_f32_e32 v1, v15, v1
	v_cvt_pk_bf16_f32 v0, v0, v1
	v_mul_f32_e32 v1, v34, v14
	v_mul_f32_e32 v1, v1, v2
	v_mul_f32_e32 v2, v35, v14
	v_mul_f32_e32 v2, v2, v3
	v_cvt_pk_bf16_f32 v1, v1, v2
	ds_write_b64 v174, v[0:1] offset:64
	ds_read_b128 v[0:3], v154 offset:160
	v_mul_f32_e32 v15, v66, v14
	s_waitcnt lgkmcnt(0)
	v_mul_f32_e32 v0, v15, v0
	v_mul_f32_e32 v15, v36, v14
	v_mul_f32_e32 v1, v15, v1
	v_cvt_pk_bf16_f32 v0, v0, v1
	v_mul_f32_e32 v1, v68, v14
	v_mul_f32_e32 v1, v1, v2
	v_mul_f32_e32 v2, v39, v14
	v_mul_f32_e32 v2, v2, v3
	v_cvt_pk_bf16_f32 v1, v1, v2
	ds_write_b64 v174, v[0:1] offset:80
	ds_read_b128 v[0:3], v154 offset:192
	v_mul_f32_e32 v15, v38, v14
	s_waitcnt lgkmcnt(0)
	v_mul_f32_e32 v0, v15, v0
	v_mul_f32_e32 v15, v37, v14
	v_mul_f32_e32 v1, v15, v1
	v_cvt_pk_bf16_f32 v0, v0, v1
	v_mul_f32_e32 v1, v41, v14
	v_mul_f32_e32 v1, v1, v2
	v_mul_f32_e32 v2, v40, v14
	v_mul_f32_e32 v2, v2, v3
	v_cvt_pk_bf16_f32 v1, v1, v2
	ds_write_b64 v174, v[0:1] offset:96
	ds_read_b128 v[0:3], v154 offset:224
	v_mul_f32_e32 v15, v43, v14
	s_waitcnt lgkmcnt(0)
	v_mul_f32_e32 v0, v15, v0
	v_mul_f32_e32 v15, v42, v14
	v_mul_f32_e32 v1, v15, v1
	v_cvt_pk_bf16_f32 v0, v0, v1
	v_mul_f32_e32 v1, v69, v14
	v_mul_f32_e32 v1, v1, v2
	v_mul_f32_e32 v2, v46, v14
	v_mul_f32_e32 v2, v2, v3
	v_cvt_pk_bf16_f32 v1, v1, v2
	ds_write_b64 v174, v[0:1] offset:112
	ds_read_b128 v[0:3], v154 offset:256
	v_mul_f32_e32 v15, v45, v14
	s_waitcnt lgkmcnt(0)
	v_mul_f32_e32 v0, v15, v0
	v_mul_f32_e32 v15, v44, v14
	v_mul_f32_e32 v1, v15, v1
	v_cvt_pk_bf16_f32 v0, v0, v1
	v_mul_f32_e32 v1, v47, v14
	v_mul_f32_e32 v1, v1, v2
	v_mul_f32_e32 v2, v18, v14
	v_mul_f32_e32 v2, v2, v3
	v_cvt_pk_bf16_f32 v1, v1, v2
	ds_write_b64 v174, v[0:1] offset:128
	ds_read_b128 v[0:3], v154 offset:288
	v_mul_f32_e32 v15, v20, v14
	s_waitcnt lgkmcnt(0)
	v_mul_f32_e32 v0, v15, v0
	v_mul_f32_e32 v15, v19, v14
	v_mul_f32_e32 v1, v15, v1
	v_cvt_pk_bf16_f32 v0, v0, v1
	v_mul_f32_e32 v1, v70, v14
	v_mul_f32_e32 v1, v1, v2
	v_mul_f32_e32 v2, v23, v14
	v_mul_f32_e32 v2, v2, v3
	v_cvt_pk_bf16_f32 v1, v1, v2
	ds_write_b64 v174, v[0:1] offset:144
	ds_read_b128 v[0:3], v154 offset:320
	v_mul_f32_e32 v15, v22, v14
	s_waitcnt lgkmcnt(0)
	v_mul_f32_e32 v0, v15, v0
	v_mul_f32_e32 v15, v21, v14
	v_mul_f32_e32 v1, v15, v1
	v_cvt_pk_bf16_f32 v0, v0, v1
	v_mul_f32_e32 v1, v25, v14
	v_mul_f32_e32 v1, v1, v2
	v_mul_f32_e32 v2, v24, v14
	v_mul_f32_e32 v2, v2, v3
	v_cvt_pk_bf16_f32 v1, v1, v2
	ds_write_b64 v174, v[0:1] offset:160
	ds_read_b128 v[0:3], v154 offset:352
	v_mul_f32_e32 v15, v27, v14
	s_waitcnt lgkmcnt(0)
	v_mul_f32_e32 v0, v15, v0
	v_mul_f32_e32 v15, v26, v14
	v_mul_f32_e32 v1, v15, v1
	v_cvt_pk_bf16_f32 v0, v0, v1
	v_mul_f32_e32 v1, v71, v14
	v_mul_f32_e32 v1, v1, v2
	v_mul_f32_e32 v2, v30, v14
	v_mul_f32_e32 v2, v2, v3
	v_cvt_pk_bf16_f32 v1, v1, v2
	ds_write_b64 v174, v[0:1] offset:176
	ds_read_b128 v[0:3], v154 offset:384
	v_mul_f32_e32 v15, v29, v14
	s_waitcnt lgkmcnt(0)
	v_mul_f32_e32 v0, v15, v0
	v_mul_f32_e32 v15, v28, v14
	v_mul_f32_e32 v1, v15, v1
	v_cvt_pk_bf16_f32 v0, v0, v1
	v_mul_f32_e32 v1, v72, v14
	v_mul_f32_e32 v1, v1, v2
	v_mul_f32_e32 v2, v31, v14
	v_mul_f32_e32 v2, v2, v3
	v_cvt_pk_bf16_f32 v1, v1, v2
	ds_write_b64 v174, v[0:1] offset:192
	ds_read_b128 v[0:3], v154 offset:416
	v_mul_f32_e32 v15, v74, v14
	s_waitcnt lgkmcnt(0)
	v_mul_f32_e32 v0, v15, v0
	v_mul_f32_e32 v15, v73, v14
	v_mul_f32_e32 v1, v15, v1
	v_cvt_pk_bf16_f32 v0, v0, v1
	v_mul_f32_e32 v1, v6, v14
	v_mul_f32_e32 v1, v1, v2
	v_mul_f32_e32 v2, v7, v14
	v_mul_f32_e32 v2, v2, v3
	v_cvt_pk_bf16_f32 v1, v1, v2
	ds_write_b64 v174, v[0:1] offset:208
	ds_read_b128 v[0:3], v154 offset:448
	s_waitcnt lgkmcnt(0)
	v_mul_f32_e32 v0, v4, v0
	v_mul_f32_e32 v4, v5, v14
	v_mul_f32_e32 v1, v4, v1
	v_cvt_pk_bf16_f32 v0, v0, v1
	v_mul_f32_e32 v1, v8, v14
	v_mul_f32_e32 v1, v1, v2
	v_mul_f32_e32 v2, v9, v14
	v_mul_f32_e32 v2, v2, v3
	v_cvt_pk_bf16_f32 v1, v1, v2
	ds_write_b64 v174, v[0:1] offset:224
	ds_read_b128 v[0:3], v154 offset:480
	v_mul_f32_e32 v4, v10, v14
	s_waitcnt lgkmcnt(0)
	v_mul_f32_e32 v0, v4, v0
	v_mul_f32_e32 v4, v11, v14
	v_mul_f32_e32 v1, v4, v1
	v_cvt_pk_bf16_f32 v0, v0, v1
	v_mul_f32_e32 v1, v12, v14
	v_mul_f32_e32 v1, v1, v2
	v_mul_f32_e32 v2, v13, v14
	v_mul_f32_e32 v2, v2, v3
	v_cvt_pk_bf16_f32 v1, v1, v2
	ds_write_b64 v174, v[0:1] offset:240
	v_or_b32_e32 v0, s34, v166
	v_or_b32_e32 v8, s35, v0
	ds_read_b128 v[0:3], v187
	v_or_b32_e32 v6, v8, v175
	v_lshl_add_u64 v[4:5], v[152:153], 0, s[36:37]
	v_lshlrev_b32_e32 v208, 11, v6
	v_lshl_add_u64 v[6:7], v[4:5], 0, v[208:209]
	s_waitcnt lgkmcnt(0)
	global_store_dwordx4 v[6:7], v[0:3], off
	ds_read_b128 v[0:3], v187 offset:1088
	v_or_b32_e32 v6, v8, v176
	v_lshlrev_b32_e32 v208, 11, v6
	v_lshl_add_u64 v[6:7], v[4:5], 0, v[208:209]
	s_waitcnt lgkmcnt(0)
	global_store_dwordx4 v[6:7], v[0:3], off
	ds_read_b128 v[0:3], v187 offset:2176
	v_or_b32_e32 v6, v8, v177
	v_lshlrev_b32_e32 v208, 11, v6
	v_lshl_add_u64 v[6:7], v[4:5], 0, v[208:209]
	s_waitcnt lgkmcnt(0)
	global_store_dwordx4 v[6:7], v[0:3], off
	ds_read_b128 v[0:3], v188
	v_or_b32_e32 v6, v8, v178
	v_lshlrev_b32_e32 v208, 11, v6
	v_lshl_add_u64 v[6:7], v[4:5], 0, v[208:209]
	s_waitcnt lgkmcnt(0)
	global_store_dwordx4 v[6:7], v[0:3], off
	ds_read_b128 v[0:3], v187 offset:4352
	v_or_b32_e32 v6, v8, v179
	v_lshlrev_b32_e32 v208, 11, v6
	v_lshl_add_u64 v[6:7], v[4:5], 0, v[208:209]
	s_waitcnt lgkmcnt(0)
	global_store_dwordx4 v[6:7], v[0:3], off
	ds_read_b128 v[0:3], v187 offset:5440
	v_or_b32_e32 v6, v8, v180
	v_lshlrev_b32_e32 v208, 11, v6
	v_lshl_add_u64 v[6:7], v[4:5], 0, v[208:209]
	s_waitcnt lgkmcnt(0)
	global_store_dwordx4 v[6:7], v[0:3], off
	ds_read_b128 v[0:3], v187 offset:6528
	v_or_b32_e32 v6, v8, v181
	v_lshlrev_b32_e32 v208, 11, v6
	v_lshl_add_u64 v[6:7], v[4:5], 0, v[208:209]
	s_waitcnt lgkmcnt(0)
	global_store_dwordx4 v[6:7], v[0:3], off
	ds_read_b128 v[0:3], v189
	v_or_b32_e32 v6, v8, v182
	v_lshlrev_b32_e32 v208, 11, v6
	v_lshl_add_u64 v[4:5], v[4:5], 0, v[208:209]
	s_waitcnt lgkmcnt(0)
	global_store_dwordx4 v[4:5], v[0:3], off
	s_branch .LBB0_739
